# indexer: after the score barrier each wave touches the next group's q/w row and first key tile (one dword load to a dead VGPR) so the next prologue hits L2
# baseline (speedup 1.0000x reference)
; #define LAS __attribute__((address_space(3)))
; __device__ __forceinline__ void indexer_phase(const bf16_t* PJ, float* rk, unsigned short* SEL, LAS unsigned char* lds) {
;     ...
;     for (int gl = blockIdx.x; gl < TOK / 8; gl += gridDim.x) {
;         const int b = gl >> 9, jj = gl & 511, t0 = (jj < 256 ? jj : 767 - jj) * 8;
;         const size_t rowbase = (size_t)b * SEQ;
;         const int t = t0 + wid;
;         unsigned short* selrow = SEL + (rowbase + t) * 256;
;         if (t0 + 7 < 256) {
; #pragma unroll
;             for (int i = 0; i < 4; ++i) { const int s = lane + 64 * i; selrow[s] = (unsigned short)(s <= t ? s : 0); }
;             continue;
;         }
;         {
;             const int g = r32 >> 3, hp = (r32 >> 2) & 1, ii = r32 & 3, tq = 2 * hp + (g >> 1), head = 4 * (g & 1) + ii;
;             bf16x8 af[2][4]; float wq[2][2][8];
; #pragma unroll
;             for (int rt = 0; rt < 2; ++rt) {
;                 const bf16_t* qp = PJ + (rowbase + t0 + 4 * rt + tq) * PROJ_LD + PJ_QI + head * 64 + hi * 8;
; #pragma unroll
;                 for (int kk = 0; kk < 4; ++kk) af[rt][kk] = *(const bf16x8*)(qp + kk * 16);
; #pragma unroll
;                 for (int qq = 0; qq < 2; ++qq) { const u32x4 w = *(const u32x4*)(PJ + (rowbase + t0 + 4 * rt + 2 * hi + qq) * PROJ_LD + PJ_WI);
;     ...
;         __syncthreads();
;         {
;             const LAS float* row = (const LAS float*)lds + wid * 4096;
;             float vmax = -INFINITY, vmin = INFINITY;
; #pragma unroll
;             for (int w = 0; w < NWAVE; ++w) { vmax = fmaxf(vmax, pmm[(w * 8 + wid) * 2]); vmin = fminf(vmin, pmm[(w * 8 + wid) * 2 + 1]); }
;             const int nI4 = (t >> 8) + 1;
;             float lo = vmin, sc = (vmax > vmin) ? 511.f / (vmax - vmin) : 0.f;
.LBB0_882:
	s_or_b64 exec, exec, s[24:25]
	v_readlane_b32 s0, v255, 23
	s_add_i32 s0, s0, 0
	s_add_i32 s0, s0, 0x26000
	v_mov_b32_e32 v1, s0
	s_waitcnt lgkmcnt(0)
	s_barrier
	s_add_i32 s32, s2, s72
	s_cmpk_lt_i32 s32, 0x1000
	s_cbranch_scc0 .Lidx_notouch
	s_and_b32 s98, s32, 0x1ff
	s_sub_i32 s99, 0x2ff, s98
	s_cmpk_lt_u32 s98, 0x100
	s_cselect_b32 s98, s98, s99
	s_lshl_b32 s98, s98, 3
	s_lshr_b32 s99, s32, 9
	s_lshl_b32 s99, s99, 12
	s_add_i32 s98, s98, s99
	s_add_i32 s98, s98, s33
	s_lshl_b32 s32, s33, 5
	s_add_i32 s99, s99, s32
	v_readlane_b32 s100, v255, 13
	v_readlane_b32 s101, v255, 14
	v_add_u32_e32 v248, s99, v108
	v_mov_b32_e32 v249, 0x1500
	v_subrev_u32_e32 v250, 32, v108
	v_lshlrev_b32_e32 v250, 7, v250
	v_add_u32_e32 v250, 0x1100, v250
	v_cmp_gt_u32_e32 vcc, 32, v108
	v_mov_b32_e32 v251, s98
	v_mov_b32_e32 v252, s100
	v_mov_b32_e32 v253, s101
	v_cndmask_b32_e32 v248, v251, v248, vcc
	v_cndmask_b32_e32 v249, v250, v249, vcc
	s_nop 0
	v_mad_u64_u32 v[252:253], s[100:101], v248, v177, v[252:253]
	s_nop 1
	v_add_co_u32_e32 v252, vcc, v252, v249
	s_nop 1
	v_addc_co_u32_e32 v253, vcc, 0, v253, vcc
	s_mov_b64 s[100:101], exec
	s_mov_b32 exec_lo, -1
	s_mov_b32 exec_hi, 0x3ff
	global_load_dword v254, v[252:253], off
	s_mov_b64 exec, s[100:101]
.Lidx_notouch:
	ds_read2_b64 v[2:5], v1 offset1:8
	ds_read2_b64 v[6:9], v1 offset0:16 offset1:24
	s_mov_b32 s0, 0xff800000
	ds_read2_b64 v[12:15], v1 offset0:32 offset1:40
	s_waitcnt lgkmcnt(2)
	v_max3_f32 v10, v2, s0, v4
	s_mov_b32 s0, 0x7f800000
	v_min3_f32 v16, v3, s0, v5
	ds_read2_b64 v[2:5], v1 offset0:48 offset1:56
	s_waitcnt lgkmcnt(2)
	v_max3_f32 v1, v10, v6, v8
	v_min3_f32 v6, v16, v7, v9
	s_waitcnt lgkmcnt(1)
	v_max3_f32 v1, v1, v12, v14
	v_min3_f32 v6, v6, v13, v15
	s_waitcnt lgkmcnt(0)
	v_max3_f32 v1, v1, v2, v4
	v_min3_f32 v4, v6, v3, v5
	v_cmp_ngt_f32_e32 vcc, v1, v4
	v_mov_b32_e32 v5, 0
	v_mov_b32_e32 v6, 0
	s_cbranch_vccnz .LBB0_884
	v_sub_f32_e32 v1, v1, v4
	v_div_scale_f32 v2, s[0:1], v1, v1, s45
	v_rcp_f32_e32 v3, v2
	v_div_scale_f32 v6, vcc, s45, v1, s45
	v_fma_f32 v7, -v2, v3, 1.0
	v_fmac_f32_e32 v3, v7, v3
	v_mul_f32_e32 v7, v6, v3
	v_fma_f32 v8, -v2, v7, v6
	v_fmac_f32_e32 v7, v8, v3
	v_fma_f32 v2, -v2, v7, v6
	v_div_fmas_f32 v2, v2, v3, v7
	v_div_fixup_f32 v6, v2, v1, s45
